# v20 + merge epilogues hand-rewritten + P1 accumulator zeroing peeled into first K iteration
# speedup vs baseline: 1.0071x; 1.0016x over previous
.LBB0_537:
	s_or_b64 exec, exec, s[0:1]
	s_and_b64 s[0:1], s[36:37], exec
	s_cselect_b32 s28, 16, 0x1000
	s_add_u32 s64, s76, 0x13d00000
	s_addc_u32 s65, s77, 0
	s_bfe_u32 s68, s96, 0x20006
	s_mul_i32 s0, s68, 0x3700
	s_add_i32 s71, s0, 0
	s_and_b32 s0, s96, 0xffffff00
	s_lshr_b32 s74, s96, 8
	s_add_i32 s84, s0, 0
	s_lshl_b32 s11, s74, 5
	s_add_i32 s80, s84, 0x12600
	s_cmpk_lt_u32 s96, 0x540
	v_readlane_b32 s20, v255, 31
	s_cselect_b64 s[40:41], -1, 0
	s_add_i32 s12, s20, -4
	s_lshl_b32 s13, s12, 2
	s_lshl_b32 s22, s12, 10
	s_cmpk_lt_u32 s96, 0x440
	s_cselect_b64 s[42:43], -1, 0
	s_lshl_b32 s66, s20, 10
	s_cmpk_lt_u32 s96, 0x340
	s_cselect_b64 s[46:47], -1, 0
	s_add_i32 s14, s20, 4
	s_lshl_b32 s15, s14, 2
	s_lshl_b32 s23, s14, 10
	s_cmpk_lt_u32 s96, 0x240
	s_cselect_b64 s[48:49], -1, 0
	s_add_i32 s16, s20, 8
	s_lshl_b32 s17, s16, 2
	s_lshl_b32 s24, s16, 10
	s_cmp_eq_u32 s20, 4
	s_cselect_b64 s[50:51], -1, 0
	s_cmp_eq_u32 s20, 2
	s_mov_b32 s0, 0xfc00000
	s_cselect_b32 s38, s0, 0x13d00000
	s_add_u32 s8, s76, s6
	s_addc_u32 s9, s77, 0
	s_mul_i32 s0, s20, 0x2400
	s_add_i32 s1, 0, 0x1a900
	s_add_i32 s81, s1, s0
	s_lshl_b32 s0, s74, 7
	s_add_i32 s83, s0, 0
	s_add_i32 s82, s81, 0x2000
	s_add_i32 s83, s83, 0x14800
	s_add_i32 s84, s84, 0x12400
	s_lshl_b32 s29, s20, 5
	s_add_u32 s6, s64, s6
	s_addc_u32 s7, s65, 0
	s_lshl_b32 s85, s33, 10
	s_add_u32 s18, s76, 0x10000
	v_writelane_b32 v255, s96, 33
	s_addc_u32 s19, s77, 0
	v_lshl_or_b32 v11, s68, 4, v9
	v_writelane_b32 v255, s18, 34
	v_add_u32_e32 v25, 1, v11
	v_lshlrev_b32_e32 v27, 3, v38
	v_writelane_b32 v255, s19, 35
	v_lshlrev_b32_e32 v10, 7, v25
	v_and_b32_e32 v22, 8, v27
	s_add_i32 s0, 0, 0x1cd00
	s_add_i32 s18, 0, 0x1f100
	v_add3_u32 v91, s1, v10, v22
	v_add3_u32 v92, s0, v10, v22
	v_add3_u32 v93, s18, v10, v22
	v_lshlrev_b32_e32 v10, 8, v25
	s_add_i32 s19, 0, 0x23900
	v_add3_u32 v28, s19, v10, v22
	v_lshlrev_b32_e32 v10, 7, v11
	v_add3_u32 v94, s1, v10, v22
	v_add3_u32 v95, s0, v10, v22
	v_add3_u32 v96, s18, v10, v22
	v_lshlrev_b32_e32 v10, 8, v11
	v_add3_u32 v29, s19, v10, v22
	v_add_u32_e32 v10, 1, v89
	s_add_i32 s19, 0, 0x21500
	v_lshl_add_u32 v32, v10, 7, s19
	v_xor_b32_e32 v10, v10, v39
	v_lshlrev_b32_e32 v10, 4, v10
	v_and_b32_e32 v33, 0x70, v10
	v_lshlrev_b32_e32 v10, 7, v89
	v_add_u32_e32 v34, s19, v10
	s_add_i32 s19, 0, 0x12800
	s_cmp_lg_u32 s12, 16
	v_add_u32_e32 v36, s19, v10
	v_or_b32_e32 v10, s13, v38
	s_cselect_b64 vcc, -1, 0
	v_xor_b32_e32 v22, v89, v39
	v_cndmask_b32_e32 v98, 64, v10, vcc
	v_bitop3_b32 v10, v38, v39, s13 bitop3:0x36
	v_lshlrev_b32_e32 v22, 4, v22
	v_and_or_b32 v10, v10, 7, v41
	v_and_b32_e32 v35, 0x70, v22
	v_lshlrev_b32_e32 v22, 4, v10
	v_mov_b32_e32 v10, 0
	v_mov_b32_e32 v23, v10
	s_cmp_lg_u32 s20, 16
	v_lshl_add_u64 v[48:49], s[4:5], 0, v[22:23]
	v_or_b32_e32 v22, s3, v38
	s_cselect_b64 vcc, -1, 0
	v_cndmask_b32_e32 v99, 64, v22, vcc
	v_bitop3_b32 v22, v38, v39, s3 bitop3:0x36
	v_and_or_b32 v22, v22, 7, v41
	v_lshlrev_b32_e32 v22, 4, v22
	s_cmp_lg_u32 s14, 16
	v_lshl_add_u64 v[50:51], s[4:5], 0, v[22:23]
	v_or_b32_e32 v22, s15, v38
	s_cselect_b64 vcc, -1, 0
	v_cndmask_b32_e32 v100, 64, v22, vcc
	v_bitop3_b32 v22, v38, v39, s15 bitop3:0x36
	v_and_or_b32 v22, v22, 7, v41
	v_lshlrev_b32_e32 v22, 4, v22
	s_cmp_lg_u32 s16, 16
	v_lshl_add_u64 v[52:53], s[4:5], 0, v[22:23]
	v_or_b32_e32 v22, s17, v38
	s_cselect_b64 vcc, -1, 0
	v_cndmask_b32_e32 v101, 64, v22, vcc
	v_bitop3_b32 v22, v38, v39, s17 bitop3:0x36
	v_and_or_b32 v22, v22, 7, v41
	v_lshlrev_b32_e32 v22, 4, v22
	v_lshl_add_u64 v[54:55], s[4:5], 0, v[22:23]
	v_xor_b32_e32 v22, v38, v20
	s_movk_i32 s10, 0x3700
	v_or_b32_e32 v22, v22, v41
	v_lshlrev_b32_e32 v41, 5, v9
	v_lshrrev_b32_e32 v45, 7, v42
	v_cmp_gt_u32_e64 s[0:1], 16, v40
	v_or_b32_e32 v103, v27, v41
	v_lshl_add_u32 v104, v40, 2, s71
	v_add_u32_e32 v40, s71, v41
	v_lshrrev_b32_e32 v41, 2, v9
	v_mul_lo_u32 v45, v45, s10
	v_or_b32_e32 v41, v90, v41
	v_add_u32_e32 v67, 0, v45
	v_bfe_u32 v45, v42, 3, 4
	v_mul_u32_u24_e32 v41, 0x48, v41
	v_and_b32_e32 v21, 12, v21
	v_mul_u32_u24_e32 v45, 0x48, v45
	v_or_b32_e32 v24, s11, v90
	v_add_lshl_u32 v105, v21, v41, 1
	v_lshl_or_b32 v21, v89, 6, v8
	v_add_lshl_u32 v8, v45, v8, 1
	v_mov_b32_e32 v45, v10
	v_and_b32_e32 v26, 7, v25
	v_lshl_add_u64 v[60:61], s[6:7], 0, v[44:45]
	v_cmp_eq_u32_e64 s[6:7], 0, v42
	v_lshrrev_b32_e32 v42, 3, v24
	v_and_b32_e32 v62, 8, v42
	v_bitop3_b32 v63, v42, v26, 5 bitop3:0x6c
	v_or_b32_e32 v63, v63, v62
	v_lshlrev_b32_e32 v68, 4, v63
	v_add_u32_e32 v63, 64, v24
	v_bitop3_b32 v45, v42, v25, 7 bitop3:0x78
	v_lshrrev_b32_e32 v64, 3, v63
	v_xor_b32_e32 v69, v42, v20
	v_bitop3_b32 v42, v42, v20, 5 bitop3:0x6c
	v_and_b32_e32 v65, 8, v64
	v_or_b32_e32 v42, v42, v62
	v_bitop3_b32 v62, v64, v20, 5 bitop3:0x6c
	v_or_b32_e32 v62, v62, v65
	v_lshlrev_b32_e32 v108, 4, v69
	v_lshlrev_b32_e32 v69, 4, v62
	v_or_b32_e32 v62, 16, v24
	v_lshlrev_b32_e32 v22, 4, v22
	v_lshlrev_b32_e32 v71, 1, v63
	v_lshrrev_b32_e32 v63, 3, v62
	v_lshl_add_u64 v[56:57], s[4:5], 0, v[22:23]
	v_xor_b32_e32 v22, v88, v20
	v_bitop3_b32 v26, v64, v26, 5 bitop3:0x6c
	v_bitop3_b32 v64, v63, v25, 7 bitop3:0x78
	v_lshlrev_b32_e32 v22, 4, v22
	v_or_b32_e32 v26, v26, v65
	v_lshlrev_b32_e32 v111, 4, v64
	v_and_b32_e32 v64, 8, v63
	v_bitop3_b32 v65, v63, v25, 7 bitop3:0x28
	s_movk_i32 s18, 0x48
	v_lshl_add_u64 v[58:59], s[8:9], 0, v[22:23]
	v_or_b32_e32 v23, s11, v9
	v_or_b32_e32 v65, v65, v64
	v_mul_u32_u24_e32 v30, 0x48, v11
	v_mul_u32_u24_e32 v31, 0x48, v9
	v_lshlrev_b32_e32 v97, 2, v11
	v_or_b32_e32 v22, 16, v90
	v_lshlrev_b32_e32 v72, 4, v65
	v_add_u32_e32 v65, 0x50, v24
	v_mul_lo_u32 v23, v23, s18
	v_mad_u32_u24 v11, v11, s18, 32
	v_lshlrev_b32_e32 v70, 1, v24
	v_add_lshl_u32 v109, v24, v30, 1
	v_add_lshl_u32 v110, v24, v31, 1
	v_lshrrev_b32_e32 v73, 3, v65
	v_xor_b32_e32 v75, v63, v20
	v_bitop3_b32 v63, v63, v20, 7 bitop3:0x6c
	v_add_lshl_u32 v113, v62, v30, 1
	v_add_lshl_u32 v115, v30, v90, 1
	v_add_lshl_u32 v116, v22, v30, 1
	v_add_u32_e32 v30, 0x480, v23
	v_add_lshl_u32 v119, v11, v90, 1
	v_add_lshl_u32 v120, v11, v22, 1
	v_or_b32_e32 v11, 32, v90
	v_lshlrev_b32_e32 v123, 2, v24
	v_or_b32_e32 v24, 1, v90
	v_cmp_eq_u32_e32 vcc, v90, v9
	v_lshlrev_b32_e32 v106, 5, v20
	v_and_b32_e32 v74, 8, v73
	v_bitop3_b32 v25, v73, v25, 7 bitop3:0x28
	v_or_b32_e32 v63, v63, v64
	v_bitop3_b32 v20, v73, v20, 7 bitop3:0x6c
	v_lshlrev_b32_e32 v73, 1, v62
	v_add_lshl_u32 v114, v62, v31, 1
	v_add_lshl_u32 v118, v30, v90, 1
	v_add_lshl_u32 v122, v11, v30, 1
	v_lshlrev_b32_e32 v124, 2, v62
	v_or_b32_e32 v30, 2, v90
	v_cndmask_b32_e64 v62, 0, 1.0, vcc
	v_cmp_eq_u32_e32 vcc, v24, v9
	v_lshlrev_b32_e32 v112, 4, v75
	v_lshlrev_b32_e32 v75, 4, v63
	v_add_lshl_u32 v117, v90, v23, 1
	v_add_lshl_u32 v121, v11, v23, 1
	v_add_lshl_u32 v125, v90, v31, 1
	v_add_lshl_u32 v23, v11, v31, 1
	v_or_b32_e32 v31, 3, v90
	v_cndmask_b32_e64 v63, 0, 1.0, vcc
	v_cmp_eq_u32_e32 vcc, v30, v9
	v_cmp_eq_u32_e64 s[4:5], 0, v9
	v_mad_u32_u24 v37, v9, s18, 16
	v_cmp_lt_u32_e64 s[8:9], v90, v9
	v_cmp_gt_u32_e64 s[10:11], v90, v9
	v_cmp_lt_u32_e64 s[12:13], v24, v9
	v_cmp_lt_u32_e64 s[14:15], v30, v9
	v_cmp_gt_u32_e64 s[16:17], v30, v9
	v_cmp_lt_u32_e64 s[18:19], v31, v9
	v_cmp_gt_u32_e64 s[20:21], v31, v9
	v_cndmask_b32_e64 v64, 0, 1.0, vcc
	v_cmp_eq_u32_e32 vcc, v31, v9
	v_lshlrev_b32_e32 v9, 2, v9
	v_lshl_add_u32 v24, v38, 10, s97
	s_mov_b32 s3, 0xdc00
	v_add3_u32 v126, v24, v9, s3
	v_and_b32_e32 v9, 3, v39
	s_movk_i32 s25, 0x2400
	v_lshlrev_b32_e32 v43, 2, v21
	v_lshlrev_b32_e32 v21, 1, v21
	v_lshl_or_b32 v9, v9, 3, s29
	v_lshlrev_b32_e32 v24, 1, v41
	s_waitcnt lgkmcnt(0)
	s_barrier
	v_lshlrev_b32_e32 v66, 2, v89
	v_or_b32_e32 v25, v25, v74
	v_or_b32_e32 v20, v20, v74
	v_add3_u32 v128, v9, v24, s25
	v_mov_b32_e32 v9, 0x3540
	v_add_u32_e32 v151, v67, v8
	v_add_u32_e32 v8, 0, v21
	s_mov_b32 s39, 0
	v_and_b32_e32 v102, 48, v39
	v_lshlrev_b32_e32 v26, 4, v26
	v_lshlrev_b32_e32 v42, 4, v42
	v_lshlrev_b32_e32 v25, 4, v25
	v_lshlrev_b32_e32 v20, 4, v20
	v_lshlrev_b32_e32 v74, 1, v65
	v_add_lshl_u32 v22, v37, v90, 1
	v_add_lshl_u32 v11, v11, v37, 1
	v_writelane_b32 v255, s97, 32
	v_lshl_or_b32 v129, v38, 4, v9
	s_add_i32 s3, 0, 0x15c00
	s_add_i32 s88, s22, 0
	s_add_i32 s89, s23, 0
	s_add_i32 s90, s24, 0
	v_add_u32_e32 v9, 0, v66
	v_add_u32_e32 v152, 0x12800, v8
	v_mbcnt_lo_u32_b32 v8, -1, 0
	s_mov_b64 s[52:53], s[38:39]
	v_add_u32_e32 v107, s70, v89
	v_lshlrev_b32_e32 v45, 4, v45
	v_cndmask_b32_e64 v65, 0, 1.0, vcc
	v_add_u32_e32 v127, 0x2d00, v103
	v_writelane_b32 v255, s29, 44
	v_or_b32_e32 v130, 0x3500, v102
	v_add_u32_e32 v131, v28, v68
	v_add_u32_e32 v132, v28, v26
	v_add_u32_e32 v133, v29, v42
	v_add_u32_e32 v134, v29, v69
	v_add_u32_e32 v135, s3, v70
	v_add_u32_e32 v136, s3, v71
	s_mov_b32 s86, 0x4038aa3b
	s_add_i32 s67, 0, 0x10000
	v_add_u32_e32 v137, v28, v72
	v_add_u32_e32 v138, v28, v25
	v_add_u32_e32 v139, v29, v75
	v_add_u32_e32 v140, v29, v20
	v_add_u32_e32 v141, s3, v73
	v_add_u32_e32 v142, s3, v74
	v_add_u32_e32 v143, v32, v33
	v_add_u32_e32 v145, v34, v35
	s_mov_b32 s87, 0xbfb8aa3b
	v_add_u32_e32 v146, v36, v44
	s_add_i32 s88, s88, 0x23900
	s_add_i32 s89, s89, 0x23900
	s_add_i32 s90, s90, 0x23900
	s_add_i32 s91, 0, 0x27900
	s_add_i32 s92, s81, 0x400
	s_add_i32 s93, s81, 0x800
	s_add_i32 s94, s81, 0xc00
	s_add_i32 s95, s81, 0x1400
	s_add_i32 s96, s81, 0x1800
	s_add_i32 s97, s81, 0x1c00
	s_add_i32 s3, 0, 0x16100
	s_add_i32 s69, 0, 0x18500
	v_mov_b32_e32 v147, 0xbf92477c
	v_add_u32_e32 v148, v40, v27
	s_xor_b64 s[54:55], s[26:27], -1
	v_add_u32_e32 v149, 0, v43
	v_add_u32_e32 v150, 0x12400, v9
	v_mov_b32_e32 v153, 0x3a27c5ac
	v_mbcnt_hi_u32_b32 v144, -1, v8
	v_add_u32_e32 v154, s71, v22
	v_add_u32_e32 v155, s71, v23
	v_add_u32_e32 v156, s71, v11
	s_mov_b32 s33, s28
	s_mov_b32 s29, 0
	v_add_u32_e32 v216, v94, v112
	v_xor_b32_e32 v242, 16, v144
	v_and_b32_e32 v241, 64, v144
	v_add_u32_e32 v21, 64, v241
	v_cmp_lt_i32_e32 vcc, v242, v21
	s_nop 1
	v_cndmask_b32_e32 v20, v144, v242, vcc
	v_lshlrev_b32_e32 v221, 2, v20
	v_add_u32_e32 v232, s69, v118
	v_add_u32_e32 v210, v96, v108
	v_add_u32_e32 v235, s3, v121
	v_add_u32_e32 v236, s69, v121
	v_add_u32_e32 v220, v91, v111
	v_add_u32_e32 v233, s67, v119
	v_add_u32_e32 v230, s69, v117
	v_add_u32_e32 v211, v93, v45
	v_add_u32_e32 v225, 0x15d80, v44
	v_add_u32_e32 v213, s67, v109
	v_add_u32_e32 v238, s69, v122
	v_add_u32_e32 v231, s3, v118
	v_add_u32_e32 v239, 0x12600, v97
	v_or_b32_e32 v240, v102, v241
	v_add_u32_e32 v209, v95, v108
	v_add_u32_e32 v215, v92, v111
	v_add_u32_e32 v218, v96, v112
	v_add_u32_e32 v207, v92, v45
	v_add_u32_e32 v224, s71, v114
	v_add_u32_e32 v229, s3, v117
	v_add_u32_e32 v223, s67, v113
	v_add_u32_e32 v219, v93, v111
	v_xor_b32_e32 v243, 32, v144
	v_add_u32_e32 v208, v94, v108
	v_cmp_lt_i32_e32 vcc, v243, v21
	s_nop 1
	v_cndmask_b32_e32 v22, v144, v243, vcc
	v_lshlrev_b32_e32 v222, 2, v22
	v_add_u32_e32 v214, s71, v110
	v_add_u32_e32 v237, s3, v122
	v_add_u32_e32 v217, v95, v112
	v_add_u32_e32 v228, s67, v116
	v_add_u32_e32 v227, s67, v115
	v_add_u32_e32 v234, s67, v120
	v_add_u32_e32 v226, s83, v102
	v_add_u32_e32 v212, v91, v45
	s_waitcnt vmcnt(0)
